# prologue de-serialisation of the weight-conversion phase: six tiles per step loaded into separate registers, one vmcnt(0) for all twelve loads, gain multiplies deferred
# speedup vs baseline: 1.0015x; 1.0015x over previous
; DI TDesc tt_decode(const Args& a, int it) {
;   constexpr int I_GU = 16 * 88, I_D = 44 * 16, I_IN = 16 * 56, I_OUT = 16 * 16, I_L = 2 * I_GU + 2 * I_D + I_IN + I_OUT;
;   const int l = it / I_L; int r = it % I_L; unsigned char* wl = a.ws + WS_W + (size_t)l * LW_SIZE; TDesc d;
;   if (r < I_GU) { d.W0 = a.in[2] + (size_t)l * DM * FF; d.W1 = a.in[3] + (size_t)l * DM * FF; d.gk = a.in[1] + l * DM; d.WT = (bf16_t*)(wl + LW_WGU1); d.kind = 0; d.K = DM; d.N = FF; d.kt = r / 88; d.nt = r % 88; return d; } r -= I_GU;
;   if (r < I_D) { d.W0 = a.in[4] + (size_t)l * FF * DM; d.W1 = nullptr; d.gk = nullptr; d.WT = (bf16_t*)(wl + LW_WD1); d.kind = 1; d.K = FF; d.N = DM; d.kt = r / 16; d.nt = r % 16; return d; } r -= I_D;
;   if (r < I_IN) { d.W0 = a.in[6] + (size_t)l * DM * INC; d.W1 = nullptr; d.gk = a.in[5] + l * DM; d.WT = (bf16_t*)(wl + LW_WIN); d.kind = 2; d.K = DM; d.N = INC; d.kt = r / 56; d.nt = r % 56; return d; } r -= I_IN;
; DI void tt_load(const TDesc& d, f32x4 (&v)[2], int tid) {
;   const int n4 = tid & 15, np = d.nt * 64 + 4 * n4, k0 = d.kt * 64; const float* src = d.W0; int col;
;   if (d.kind == 0) { const int pn = np >> 8, r = np & 255; src = (r < 128) ? d.W0 : d.W1; col = 128 * pn + (r & 127); }
;   else if (d.kind == 1) col = np;
;   else col = (np < 1792) ? np : (np < 3328) ? np + 8 : (np < 3336) ? 1792 + (np - 3328) : -1;
; #pragma unroll
;   for (int p = 0; p < 2; ++p) { const int kk = (tid >> 4) + 32 * p;
;     v[p] = (col >= 0) ? *(const f32x4*)(src + (size_t)(k0 + kk) * d.N + col) * (d.gk ? d.gk[k0 + kk] : 1.f) : (f32x4){0.f, 0.f, 0.f, 0.f}; }
.LBB0_41:
	s_lshl_b32 s16, s31, 6
	v_cmp_lt_i32_e32 vcc, -1, v2
	v_mov_b32_e32 v53, 0
	v_mov_b32_e32 v52, 0
	v_mov_b32_e32 v57, 0
	v_mov_b32_e32 v56, 0
	v_mov_b32_e32 v55, 0
	v_mov_b32_e32 v54, 0
	v_mov_b32_e32 v59, 0
	v_mov_b32_e32 v58, 0
	v_mov_b32_e32 v84, 0
	v_mov_b32_e32 v85, 0
	v_mov_b32_e32 v86, 0
	v_mov_b32_e32 v87, 0
	v_mov_b32_e32 v88, 0
	v_mov_b32_e32 v89, 0
	v_mov_b32_e32 v90, 0
	v_mov_b32_e32 v91, 0
	s_and_saveexec_b64 s[18:19], vcc
	s_cbranch_execz .LBB0_47
	v_add_u32_e32 v8, s16, v61
	v_mov_b32_e32 v3, v11
	v_ashrrev_i32_e32 v9, 31, v8
	v_lshl_add_u64 v[6:7], v[2:3], 2, s[2:3]
	v_mul_lo_u32 v4, s24, v9
	v_mul_lo_u32 v5, s25, v8
	v_mad_u64_u32 v[2:3], s[2:3], s24, v8, 0
	v_add3_u32 v3, v3, v4, v5
	v_lshl_add_u64 v[2:3], v[2:3], 2, v[6:7]
	global_load_dwordx4 v[84:87], v[2:3], off
	s_cmp_lg_u64 s[22:23], 0
	v_mov_b32_e32 v56, 1.0
	s_cselect_b64 s[2:3], -1, 0
	s_cmp_eq_u64 s[22:23], 0
	v_lshl_add_u64 v[54:55], v[8:9], 2, s[22:23]
	v_mov_b32_e32 v52, 1.0
	s_cbranch_scc1 .LBB0_44
	global_load_dword v52, v[54:55], off
.LBB0_44:
	v_add_u32_e32 v8, 32, v8
	v_ashrrev_i32_e32 v9, 31, v8
	v_mul_lo_u32 v53, s24, v9
	v_mul_lo_u32 v57, s25, v8
	v_mad_u64_u32 v[8:9], s[22:23], s24, v8, 0
	v_add3_u32 v9, v9, v53, v57
	v_lshl_add_u64 v[6:7], v[8:9], 2, v[6:7]
	global_load_dwordx4 v[88:91], v[6:7], off
	s_andn2_b64 vcc, exec, s[2:3]
	s_cbranch_vccnz .LBB0_46
	global_load_dword v56, v[54:55], off offset:128
.LBB0_46:
.LBB0_47:
	s_or_b64 exec, exec, s[18:19]
	v_readlane_b32 s2, v254, 1
	s_add_i32 s2, s2, s78
	s_cmpk_lt_i32 s2, 0x2a00
	s_cselect_b64 s[18:19], -1, 0
	s_cmpk_gt_i32 s2, 0x29ff
	s_cbranch_scc1 .LBB0_85
	s_mul_hi_i32 s3, s2, 0x30c30c31
	s_lshr_b32 s10, s3, 31
	s_ashr_i32 s3, s3, 10
	s_add_i32 s24, s3, s10
	s_mul_i32 s3, s24, 0x1500
	s_sub_i32 s17, s2, s3
	s_ashr_i32 s25, s24, 31
	s_mul_i32 s3, s24, 0x2a00000
	s_mul_hi_i32 s2, s24, 0x2a00000
	s_add_u32 s22, s74, s3
	s_addc_u32 s23, s75, s2
	s_cmpk_lt_i32 s17, 0x580
	s_mov_b64 s[34:35], -1
	s_cbranch_scc1 .LBB0_65
	s_cmpk_lt_u32 s17, 0x840
	s_cbranch_scc1 .LBB0_62
	s_cmpk_lt_u32 s17, 0xbc0
	s_cbranch_scc1 .LBB0_59
	s_cmpk_lt_u32 s17, 0xcc0
	s_cbranch_scc1 .LBB0_56
	s_cmpk_lt_u32 s17, 0x1240
	s_mov_b64 s[26:27], -1
	s_cbranch_scc1 .LBB0_54
	s_add_i32 s26, s17, 0xffffedc0
	s_mul_i32 s2, s24, 0xb00000
	s_mul_hi_i32 s3, s24, 0xb00000
	s_add_u32 s2, s67, s2
	s_addc_u32 s3, s68, s3
	s_add_u32 s10, s22, 0x2480000
	s_addc_u32 s11, s23, 0
	s_lshr_b32 s86, s26, 4
	s_and_b32 s88, s17, 15
	s_mov_b64 s[26:27], 0

; DI void tt_load(const TDesc& d, f32x4 (&v)[2], int tid) {
;   const int n4 = tid & 15, np = d.nt * 64 + 4 * n4, k0 = d.kt * 64; const float* src = d.W0; int col;
;   if (d.kind == 0) { const int pn = np >> 8, r = np & 255; src = (r < 128) ? d.W0 : d.W1; col = 128 * pn + (r & 127); }
;   else if (d.kind == 1) col = np;
;   else col = (np < 1792) ? np : (np < 3328) ? np + 8 : (np < 3336) ? 1792 + (np - 3328) : -1;
; #pragma unroll
;   for (int p = 0; p < 2; ++p) { const int kk = (tid >> 4) + 32 * p;
;     v[p] = (col >= 0) ? *(const f32x4*)(src + (size_t)(k0 + kk) * d.N + col) * (d.gk ? d.gk[k0 + kk] : 1.f) : (f32x4){0.f, 0.f, 0.f, 0.f}; }
.LBB0_78:
	v_cmp_lt_i32_e32 vcc, -1, v2
	v_mov_b32_e32 v17, 0
	v_mov_b32_e32 v16, 0
	v_mov_b32_e32 v19, 0
	v_mov_b32_e32 v18, 0
	v_mov_b32_e32 v13, 0
	v_mov_b32_e32 v12, 0
	v_mov_b32_e32 v15, 0
	v_mov_b32_e32 v14, 0
	v_mov_b32_e32 v92, 0
	v_mov_b32_e32 v93, 0
	v_mov_b32_e32 v94, 0
	v_mov_b32_e32 v95, 0
	v_mov_b32_e32 v96, 0
	v_mov_b32_e32 v97, 0
	v_mov_b32_e32 v98, 0
	v_mov_b32_e32 v99, 0
	s_and_saveexec_b64 s[22:23], vcc
	s_cbranch_execz .LBB0_84
	v_lshl_add_u32 v8, s86, 6, v61
	v_mov_b32_e32 v3, v11
	v_ashrrev_i32_e32 v9, 31, v8
	v_lshl_add_u64 v[6:7], v[2:3], 2, s[2:3]
	v_mul_lo_u32 v4, s28, v9
	v_mul_lo_u32 v5, s29, v8
	v_mad_u64_u32 v[2:3], s[2:3], s28, v8, 0
	v_add3_u32 v3, v3, v4, v5
	v_lshl_add_u64 v[2:3], v[2:3], 2, v[6:7]
	global_load_dwordx4 v[92:95], v[2:3], off
	s_cmp_lg_u64 s[26:27], 0
	v_mov_b32_e32 v18, 1.0
	s_cselect_b64 s[2:3], -1, 0
	s_cmp_eq_u64 s[26:27], 0
	v_lshl_add_u64 v[12:13], v[8:9], 2, s[26:27]
	v_mov_b32_e32 v14, 1.0
	s_cbranch_scc1 .LBB0_81
	global_load_dword v14, v[12:13], off
.LBB0_81:
	v_add_u32_e32 v8, 32, v8
	v_ashrrev_i32_e32 v9, 31, v8
	v_mul_lo_u32 v15, s28, v9
	v_mul_lo_u32 v16, s29, v8
	v_mad_u64_u32 v[8:9], s[24:25], s28, v8, 0
	v_add3_u32 v9, v9, v15, v16
	v_lshl_add_u64 v[6:7], v[8:9], 2, v[6:7]
	global_load_dwordx4 v[96:99], v[6:7], off
	s_andn2_b64 vcc, exec, s[2:3]
	s_cbranch_vccnz .LBB0_83
	global_load_dword v18, v[12:13], off offset:128
.LBB0_83:
.LBB0_84:
	s_or_b64 exec, exec, s[22:23]

; DI void tt_load(const TDesc& d, f32x4 (&v)[2], int tid) {
;   const int n4 = tid & 15, np = d.nt * 64 + 4 * n4, k0 = d.kt * 64; const float* src = d.W0; int col;
;   if (d.kind == 0) { const int pn = np >> 8, r = np & 255; src = (r < 128) ? d.W0 : d.W1; col = 128 * pn + (r & 127); }
;   else if (d.kind == 1) col = np;
;   else col = (np < 1792) ? np : (np < 3328) ? np + 8 : (np < 3336) ? 1792 + (np - 3328) : -1;
; #pragma unroll
;   for (int p = 0; p < 2; ++p) { const int kk = (tid >> 4) + 32 * p;
;     v[p] = (col >= 0) ? *(const f32x4*)(src + (size_t)(k0 + kk) * d.N + col) * (d.gk ? d.gk[k0 + kk] : 1.f) : (f32x4){0.f, 0.f, 0.f, 0.f}; }
.LBB0_116:
	v_cmp_lt_i32_e32 vcc, -1, v2
	v_mov_b32_e32 v25, 0
	v_mov_b32_e32 v24, 0
	v_mov_b32_e32 v27, 0
	v_mov_b32_e32 v26, 0
	v_mov_b32_e32 v21, 0
	v_mov_b32_e32 v20, 0
	v_mov_b32_e32 v23, 0
	v_mov_b32_e32 v22, 0
	v_mov_b32_e32 v100, 0
	v_mov_b32_e32 v101, 0
	v_mov_b32_e32 v102, 0
	v_mov_b32_e32 v103, 0
	v_mov_b32_e32 v104, 0
	v_mov_b32_e32 v105, 0
	v_mov_b32_e32 v106, 0
	v_mov_b32_e32 v107, 0
	s_and_saveexec_b64 s[24:25], vcc
	s_cbranch_execz .LBB0_122
	v_lshl_add_u32 v8, s81, 6, v61
	v_mov_b32_e32 v3, v11
	v_ashrrev_i32_e32 v9, 31, v8
	v_lshl_add_u64 v[6:7], v[2:3], 2, s[2:3]
	v_mul_lo_u32 v4, s30, v9
	v_mul_lo_u32 v5, s31, v8
	v_mad_u64_u32 v[2:3], s[2:3], s30, v8, 0
	v_add3_u32 v3, v3, v4, v5
	v_lshl_add_u64 v[2:3], v[2:3], 2, v[6:7]
	global_load_dwordx4 v[100:103], v[2:3], off
	s_cmp_lg_u64 s[28:29], 0
	v_mov_b32_e32 v26, 1.0
	s_cselect_b64 s[2:3], -1, 0
	s_cmp_eq_u64 s[28:29], 0
	v_lshl_add_u64 v[20:21], v[8:9], 2, s[28:29]
	v_mov_b32_e32 v22, 1.0
	s_cbranch_scc1 .LBB0_119
	global_load_dword v22, v[20:21], off
.LBB0_119:
	v_add_u32_e32 v8, 32, v8
	v_ashrrev_i32_e32 v9, 31, v8
	v_mul_lo_u32 v23, s30, v9
	v_mul_lo_u32 v24, s31, v8
	v_mad_u64_u32 v[8:9], s[26:27], s30, v8, 0
	v_add3_u32 v9, v9, v23, v24
	v_lshl_add_u64 v[6:7], v[8:9], 2, v[6:7]
	global_load_dwordx4 v[104:107], v[6:7], off
	s_andn2_b64 vcc, exec, s[2:3]
	s_cbranch_vccnz .LBB0_121
	global_load_dword v26, v[20:21], off offset:128
.LBB0_121:
.LBB0_122:
	s_or_b64 exec, exec, s[24:25]

; DI void tt_load(const TDesc& d, f32x4 (&v)[2], int tid) {
;   const int n4 = tid & 15, np = d.nt * 64 + 4 * n4, k0 = d.kt * 64; const float* src = d.W0; int col;
;   if (d.kind == 0) { const int pn = np >> 8, r = np & 255; src = (r < 128) ? d.W0 : d.W1; col = 128 * pn + (r & 127); }
;   else if (d.kind == 1) col = np;
;   else col = (np < 1792) ? np : (np < 3328) ? np + 8 : (np < 3336) ? 1792 + (np - 3328) : -1;
; #pragma unroll
;   for (int p = 0; p < 2; ++p) { const int kk = (tid >> 4) + 32 * p;
;     v[p] = (col >= 0) ? *(const f32x4*)(src + (size_t)(k0 + kk) * d.N + col) * (d.gk ? d.gk[k0 + kk] : 1.f) : (f32x4){0.f, 0.f, 0.f, 0.f}; }
.LBB0_154:
	v_cmp_lt_i32_e32 vcc, -1, v2
	v_mov_b32_e32 v33, 0
	v_mov_b32_e32 v32, 0
	v_mov_b32_e32 v35, 0
	v_mov_b32_e32 v34, 0
	v_mov_b32_e32 v29, 0
	v_mov_b32_e32 v28, 0
	v_mov_b32_e32 v31, 0
	v_mov_b32_e32 v30, 0
	v_mov_b32_e32 v108, 0
	v_mov_b32_e32 v109, 0
	v_mov_b32_e32 v110, 0
	v_mov_b32_e32 v111, 0
	v_mov_b32_e32 v112, 0
	v_mov_b32_e32 v113, 0
	v_mov_b32_e32 v114, 0
	v_mov_b32_e32 v115, 0
	s_and_saveexec_b64 s[26:27], vcc
	s_cbranch_execz .LBB0_160
	v_lshl_add_u32 v8, s79, 6, v61
	v_mov_b32_e32 v3, v11
	v_ashrrev_i32_e32 v9, 31, v8
	v_lshl_add_u64 v[6:7], v[2:3], 2, s[2:3]
	v_mul_lo_u32 v4, s34, v9
	v_mul_lo_u32 v5, s35, v8
	v_mad_u64_u32 v[2:3], s[2:3], s34, v8, 0
	v_add3_u32 v3, v3, v4, v5
	v_lshl_add_u64 v[2:3], v[2:3], 2, v[6:7]
	global_load_dwordx4 v[108:111], v[2:3], off
	s_cmp_lg_u64 s[30:31], 0
	v_mov_b32_e32 v34, 1.0
	s_cselect_b64 s[2:3], -1, 0
	s_cmp_eq_u64 s[30:31], 0
	v_lshl_add_u64 v[28:29], v[8:9], 2, s[30:31]
	v_mov_b32_e32 v30, 1.0
	s_cbranch_scc1 .LBB0_157
	global_load_dword v30, v[28:29], off
.LBB0_157:
	v_add_u32_e32 v8, 32, v8
	v_ashrrev_i32_e32 v9, 31, v8
	v_mul_lo_u32 v31, s34, v9
	v_mul_lo_u32 v32, s35, v8
	v_mad_u64_u32 v[8:9], s[28:29], s34, v8, 0
	v_add3_u32 v9, v9, v31, v32
	v_lshl_add_u64 v[6:7], v[8:9], 2, v[6:7]
	global_load_dwordx4 v[112:115], v[6:7], off
	s_andn2_b64 vcc, exec, s[2:3]
	s_cbranch_vccnz .LBB0_159
	global_load_dword v34, v[28:29], off offset:128
.LBB0_159:
.LBB0_160:
	s_or_b64 exec, exec, s[26:27]

; DI void tt_load(const TDesc& d, f32x4 (&v)[2], int tid) {
;   const int n4 = tid & 15, np = d.nt * 64 + 4 * n4, k0 = d.kt * 64; const float* src = d.W0; int col;
;   if (d.kind == 0) { const int pn = np >> 8, r = np & 255; src = (r < 128) ? d.W0 : d.W1; col = 128 * pn + (r & 127); }
;   else if (d.kind == 1) col = np;
;   else col = (np < 1792) ? np : (np < 3328) ? np + 8 : (np < 3336) ? 1792 + (np - 3328) : -1;
; #pragma unroll
;   for (int p = 0; p < 2; ++p) { const int kk = (tid >> 4) + 32 * p;
;     v[p] = (col >= 0) ? *(const f32x4*)(src + (size_t)(k0 + kk) * d.N + col) * (d.gk ? d.gk[k0 + kk] : 1.f) : (f32x4){0.f, 0.f, 0.f, 0.f}; }
.LBB0_192:
	v_cmp_lt_i32_e32 vcc, -1, v2
	v_mov_b32_e32 v41, 0
	v_mov_b32_e32 v40, 0
	v_mov_b32_e32 v43, 0
	v_mov_b32_e32 v42, 0
	v_mov_b32_e32 v37, 0
	v_mov_b32_e32 v36, 0
	v_mov_b32_e32 v39, 0
	v_mov_b32_e32 v38, 0
	v_mov_b32_e32 v116, 0
	v_mov_b32_e32 v117, 0
	v_mov_b32_e32 v118, 0
	v_mov_b32_e32 v119, 0
	v_mov_b32_e32 v120, 0
	v_mov_b32_e32 v121, 0
	v_mov_b32_e32 v122, 0
	v_mov_b32_e32 v123, 0
	s_and_saveexec_b64 s[28:29], vcc
	s_cbranch_execz .LBB0_198
	v_lshl_add_u32 v8, s80, 6, v61
	v_mov_b32_e32 v3, v11
	v_ashrrev_i32_e32 v9, 31, v8
	v_lshl_add_u64 v[6:7], v[2:3], 2, s[26:27]
	v_mul_lo_u32 v4, s36, v9
	v_mul_lo_u32 v5, s37, v8
	v_mad_u64_u32 v[2:3], s[26:27], s36, v8, 0
	v_add3_u32 v3, v3, v4, v5
	v_lshl_add_u64 v[2:3], v[2:3], 2, v[6:7]
	global_load_dwordx4 v[116:119], v[2:3], off
	s_cmp_lg_u64 s[34:35], 0
	v_mov_b32_e32 v42, 1.0
	s_cselect_b64 s[26:27], -1, 0
	s_cmp_eq_u64 s[34:35], 0
	v_lshl_add_u64 v[36:37], v[8:9], 2, s[34:35]
	v_mov_b32_e32 v38, 1.0
	s_cbranch_scc1 .LBB0_195
	global_load_dword v38, v[36:37], off
.LBB0_195:
	v_add_u32_e32 v8, 32, v8
	v_ashrrev_i32_e32 v9, 31, v8
	v_mul_lo_u32 v39, s36, v9
	v_mul_lo_u32 v40, s37, v8
	v_mad_u64_u32 v[8:9], s[30:31], s36, v8, 0
	v_add3_u32 v9, v9, v39, v40
	v_lshl_add_u64 v[6:7], v[8:9], 2, v[6:7]
	global_load_dwordx4 v[120:123], v[6:7], off
	s_andn2_b64 vcc, exec, s[26:27]
	s_cbranch_vccnz .LBB0_197
	global_load_dword v42, v[36:37], off offset:128
.LBB0_197:
.LBB0_198:
	s_or_b64 exec, exec, s[28:29]

; #define LAUNDER(x) asm volatile("" : "+v"(x))
; DI unsigned pk2(float a, float b) { return pg8::cvt_pk_bf16(a, b); }
; DI void tt_load(const TDesc& d, f32x4 (&v)[2], int tid) {
;     ...
;     v[p] = (col >= 0) ? *(const f32x4*)(src + (size_t)(k0 + kk) * d.N + col) * (d.gk ? d.gk[k0 + kk] : 1.f) : (f32x4){0.f, 0.f, 0.f, 0.f}; }
; }
; DI void prologue_weights(const Args& a, unsigned char* lds, int tid) {
;   LAUNDER(tid);
;   constexpr int NI = 6, NITEMS = NLAYER * (2 * 16 * 88 + 2 * 44 * 16 + 16 * 56 + 16 * 16);
;   for (int it0 = blockIdx.x; it0 < NITEMS; it0 += NI * gridDim.x) {
;     f32x4 v[NI][2]; TDesc d[NI];
; #pragma unroll
;     for (int q = 0; q < NI; ++q) { const int it = it0 + q * gridDim.x; if (it < NITEMS) { d[q] = tt_decode(a, it); tt_load(d[q], v[q], tid); } }
; #pragma unroll
;     for (int q = 0; q < NI; ++q) { float* scr = (float*)lds + q * (64 * 65);
; #pragma unroll
;       for (int p = 0; p < 2; ++p) { float* w = scr + ((tid >> 4) + 32 * p) * 65 + 4 * (tid & 15); w[0] = v[q][p].x; w[1] = v[q][p].y; w[2] = v[q][p].z; w[3] = v[q][p].w; } }
;     __syncthreads();
; #pragma unroll
;     for (int q = 0; q < NI; ++q) { const int it = it0 + q * gridDim.x; if (it < NITEMS) {
;       const int n = tid >> 3, kc = tid & 7; const float* sp = (const float*)lds + q * (64 * 65) + (8 * kc) * 65 + n;
;       u32x4 o; o.x = pk2(sp[0], sp[65]); o.y = pk2(sp[2 * 65], sp[3 * 65]); o.z = pk2(sp[4 * 65], sp[5 * 65]); o.w = pk2(sp[6 * 65], sp[7 * 65]);
;       *(u32x4*)(d[q].WT + (size_t)(d[q].nt * 64 + n) * d[q].K + d[q].kt * 64 + 8 * kc) = o; } }
.LBB0_230:
	v_cmp_lt_i32_e32 vcc, -1, v2
	v_mov_b32_e32 v49, 0
	v_mov_b32_e32 v48, 0
	v_mov_b32_e32 v51, 0
	v_mov_b32_e32 v50, 0
	v_mov_b32_e32 v45, 0
	v_mov_b32_e32 v44, 0
	v_mov_b32_e32 v47, 0
	v_mov_b32_e32 v46, 0
	v_mov_b32_e32 v124, 0
	v_mov_b32_e32 v125, 0
	v_mov_b32_e32 v126, 0
	v_mov_b32_e32 v127, 0
	v_mov_b32_e32 v128, 0
	v_mov_b32_e32 v129, 0
	v_mov_b32_e32 v130, 0
	v_mov_b32_e32 v131, 0
	s_and_saveexec_b64 s[30:31], vcc
	s_cbranch_execz .LBB0_236
	v_lshl_add_u32 v8, s84, 6, v61
	v_mov_b32_e32 v3, v11
	v_ashrrev_i32_e32 v9, 31, v8
	v_lshl_add_u64 v[6:7], v[2:3], 2, s[28:29]
	v_mul_lo_u32 v4, s38, v9
	v_mul_lo_u32 v5, s39, v8
	v_mad_u64_u32 v[2:3], s[28:29], s38, v8, 0
	v_add3_u32 v3, v3, v4, v5
	v_lshl_add_u64 v[2:3], v[2:3], 2, v[6:7]
	global_load_dwordx4 v[124:127], v[2:3], off
	s_cmp_lg_u64 s[36:37], 0
	v_mov_b32_e32 v50, 1.0
	s_cselect_b64 s[28:29], -1, 0
	s_cmp_eq_u64 s[36:37], 0
	v_lshl_add_u64 v[44:45], v[8:9], 2, s[36:37]
	v_mov_b32_e32 v46, 1.0
	s_cbranch_scc1 .LBB0_233
	global_load_dword v46, v[44:45], off
.LBB0_233:
	v_add_u32_e32 v8, 32, v8
	v_ashrrev_i32_e32 v9, 31, v8
	v_mul_lo_u32 v47, s38, v9
	v_mul_lo_u32 v48, s39, v8
	v_mad_u64_u32 v[8:9], s[34:35], s38, v8, 0
	v_add3_u32 v9, v9, v47, v48
	v_lshl_add_u64 v[6:7], v[8:9], 2, v[6:7]
	global_load_dwordx4 v[128:131], v[6:7], off
	s_andn2_b64 vcc, exec, s[28:29]
	s_cbranch_vccnz .LBB0_235
	global_load_dword v50, v[44:45], off offset:128
.LBB0_235:
.LBB0_236:
	s_or_b64 exec, exec, s[30:31]
.LBB0_237:
	s_waitcnt vmcnt(0)
	v_pk_mul_f32 v[54:55], v[86:87], v[52:53] op_sel_hi:[1,0]
	v_pk_mul_f32 v[58:59], v[84:85], v[52:53] op_sel_hi:[1,0]
	v_pk_mul_f32 v[52:53], v[90:91], v[56:57] op_sel_hi:[1,0]
	v_pk_mul_f32 v[56:57], v[88:89], v[56:57] op_sel_hi:[1,0]
	v_pk_mul_f32 v[12:13], v[94:95], v[14:15] op_sel_hi:[1,0]
	v_pk_mul_f32 v[14:15], v[92:93], v[14:15] op_sel_hi:[1,0]
	v_pk_mul_f32 v[16:17], v[98:99], v[18:19] op_sel_hi:[1,0]
	v_pk_mul_f32 v[18:19], v[96:97], v[18:19] op_sel_hi:[1,0]
	v_pk_mul_f32 v[20:21], v[102:103], v[22:23] op_sel_hi:[1,0]
	v_pk_mul_f32 v[22:23], v[100:101], v[22:23] op_sel_hi:[1,0]
	v_pk_mul_f32 v[24:25], v[106:107], v[26:27] op_sel_hi:[1,0]
	v_pk_mul_f32 v[26:27], v[104:105], v[26:27] op_sel_hi:[1,0]
	v_pk_mul_f32 v[28:29], v[110:111], v[30:31] op_sel_hi:[1,0]
	v_pk_mul_f32 v[30:31], v[108:109], v[30:31] op_sel_hi:[1,0]
	v_pk_mul_f32 v[32:33], v[114:115], v[34:35] op_sel_hi:[1,0]
	v_pk_mul_f32 v[34:35], v[112:113], v[34:35] op_sel_hi:[1,0]
	v_pk_mul_f32 v[36:37], v[118:119], v[38:39] op_sel_hi:[1,0]
	v_pk_mul_f32 v[38:39], v[116:117], v[38:39] op_sel_hi:[1,0]
	v_pk_mul_f32 v[40:41], v[122:123], v[42:43] op_sel_hi:[1,0]
	v_pk_mul_f32 v[42:43], v[120:121], v[42:43] op_sel_hi:[1,0]
	v_pk_mul_f32 v[44:45], v[126:127], v[46:47] op_sel_hi:[1,0]
	v_pk_mul_f32 v[46:47], v[124:125], v[46:47] op_sel_hi:[1,0]
	v_pk_mul_f32 v[48:49], v[130:131], v[50:51] op_sel_hi:[1,0]
	v_pk_mul_f32 v[50:51], v[128:129], v[50:51] op_sel_hi:[1,0]
	v_add_u32_e32 v2, v62, v65
	v_add_u32_e32 v3, 0x2080, v2
	ds_write2_b32 v2, v58, v59 offset1:1
	ds_write2_b32 v2, v54, v55 offset0:2 offset1:3
	ds_write2_b32 v3, v56, v57 offset1:1
	v_add_u32_e32 v3, 0x2088, v2
	ds_write2_b32 v3, v52, v53 offset1:1
	v_add_u32_e32 v3, 0x4100, v2
	ds_write2_b32 v3, v14, v15 offset1:1
	v_add_u32_e32 v3, 0x4108, v2
	ds_write2_b32 v3, v12, v13 offset1:1
	v_add_u32_e32 v3, 0x6180, v2
	ds_write2_b32 v3, v18, v19 offset1:1
	v_add_u32_e32 v3, 0x6188, v2
	ds_write2_b32 v3, v16, v17 offset1:1
	v_add_u32_e32 v3, 0x8200, v2
	ds_write2_b32 v3, v22, v23 offset1:1
	v_add_u32_e32 v3, 0x8208, v2
	ds_write2_b32 v3, v20, v21 offset1:1
	v_add_u32_e32 v3, 0xa280, v2
	ds_write2_b32 v3, v26, v27 offset1:1
	v_add_u32_e32 v3, 0xa288, v2
	ds_write2_b32 v3, v24, v25 offset1:1
	v_add_u32_e32 v3, 0xc300, v2
	ds_write2_b32 v3, v30, v31 offset1:1
	v_add_u32_e32 v3, 0xc308, v2
	ds_write2_b32 v3, v28, v29 offset1:1
	v_add_u32_e32 v3, 0xe380, v2
	v_add_u32_e32 v2, 0xe388, v2
	ds_write2_b32 v3, v34, v35 offset1:1
	ds_write2_b32 v2, v32, v33 offset1:1
	ds_write2_b32 v82, v38, v39 offset1:1
	ds_write2_b32 v82, v36, v37 offset0:2 offset1:3
	v_add_u32_e32 v2, 0x2080, v82
	ds_write2_b32 v2, v42, v43 offset1:1
	v_add_u32_e32 v2, 0x2088, v82
	ds_write2_b32 v2, v40, v41 offset1:1
	ds_write2_b32 v83, v46, v47 offset1:1
	ds_write2_b32 v83, v44, v45 offset0:2 offset1:3
	v_add_u32_e32 v2, 0x2080, v83
	ds_write2_b32 v2, v50, v51 offset1:1
	v_add_u32_e32 v2, 0x2088, v83
	ds_write2_b32 v2, v48, v49 offset1:1
	s_waitcnt lgkmcnt(0)
	s_barrier
	ds_read2_b32 v[2:3], v64 offset1:65
	ds_read2_b32 v[4:5], v64 offset0:130 offset1:195
	v_add_u32_e32 v8, 0x400, v64
	ds_read2_b32 v[6:7], v8 offset0:4 offset1:69
	ds_read2_b32 v[8:9], v8 offset0:134 offset1:199
	s_ashr_i32 s17, s16, 31
	s_waitcnt lgkmcnt(3)
	v_cvt_pk_bf16_f32 v2, v2, v3
	s_waitcnt lgkmcnt(2)
	v_cvt_pk_bf16_f32 v3, v4, v5
	s_waitcnt lgkmcnt(1)
	v_cvt_pk_bf16_f32 v4, v6, v7
	v_add_u32_e32 v6, s94, v63
	v_ashrrev_i32_e32 v7, 31, v6
	s_waitcnt lgkmcnt(0)
	v_cvt_pk_bf16_f32 v5, v8, v9
	v_mul_lo_u32 v8, s14, v7
	v_mul_lo_u32 v9, s15, v6
	v_mad_u64_u32 v[6:7], s[14:15], s14, v6, 0
	v_add3_u32 v7, v7, v8, v9
	v_lshl_add_u64 v[6:7], v[6:7], 1, s[12:13]
	v_lshl_add_u64 v[6:7], s[16:17], 1, v[6:7]
	v_lshl_add_u64 v[6:7], v[6:7], 0, v[10:11]
	s_andn2_b64 vcc, exec, s[18:19]
	global_store_dwordx4 v[6:7], v[2:5], off
	s_cbranch_vccz .LBB0_242
	s_andn2_b64 vcc, exec, s[22:23]
	s_cbranch_vccz .LBB0_243
